# plus wave-half stagger in differential attention: waves 4-7 defer the scale+exp block past the mid-loop barrier
# baseline (speedup 1.0000x reference)
; __device__ __forceinline__ int opaque_tid() { int t = threadIdx.x; asm volatile("" : "+v"(t)); return t; }
; __global__ void __launch_bounds__(NTHR) mega_fwd(Params p) {
;     ...
;             const int tid = opaque_tid(), lane = tid & 63, wave = __builtin_amdgcn_readfirstlane(tid >> 6), gw = bx * NWAVES + wave; (void)tid; (void)lane; (void)gw;
;             const float lam_init = l == 0 ? 0.2f : 0.35550906759096934f;
;             float lam; { const float* lp = p.diff_lambda + l * 256; const float sa = wave_sum(lp[lane] * lp[64 + lane]), sb = wave_sum(lp[128 + lane] * lp[192 + lane]); lam = expf(sa) - expf(sb) + lam_init; }
;             constexpr float C64 = 0.125f * 1.4426950408889634f, THR64 = att::THR / 0.125f;
;             constexpr float SC128 = 0.08838834764831845f, C128 = SC128 * 1.4426950408889634f, THR128 = att::THR / SC128;
;             const int r32 = lane & 31, hi = lane >> 5;
;             unsigned* ccnt = CTL + 32768 + l * 2048;
;             if (ON_CONV && bx >= 128) {
;                 for (int ci = 0; ci < 2; ++ci) { const int item = 2 * (bx - 128) + ci;
;                     conv_tile(p, l, item, PROJ, CV, (LAS float*)(ldsl + 131072));
;                     asm volatile("s_waitcnt vmcnt(0)" ::: "memory"); __syncthreads();
;                     if (tid == 0) { __builtin_amdgcn_fence(__ATOMIC_RELEASE, "agent"); asm volatile("s_waitcnt vmcnt(0)" ::: "memory"); __hip_atomic_fetch_add(ccnt + 64 * (item >> 3), 1u, __ATOMIC_RELAXED, __HIP_MEMORY_SCOPE_AGENT); } }
;             }
;             for (int round = 0;; ++round) {
;                 const int pc = (round & 1) ? (round + 1) * G - 1 - bx : round * G + bx;
;                 if (pc >= 384) break;
;                 const int kind = pc >> 7, xq = bx & 7, b = xq >> 2, h = xq & 3, qb = (bx & 127) >> 3;
;     ...
;                 } else if (ON_NA) {
;                     { const float* rsrc = p.na_rpb + (size_t)(l * 4 + h) * 465; float* rdst = (float*)((char*)lds + att::RPB_OFF); for (int e = tid; e < 465; e += NTHR) rdst[e] = rsrc[e]; }
;                     int krow0 = 4 * qb - 4; krow0 = krow0 < 0 ? 0 : (krow0 > 52 ? 52 : krow0);
;                     const size_t rowkn = rowk + (size_t)krow0 * 64;
;                     att::attn_body<128, true, QL128, SDNA>(PROJ + rowq * NIN + PD_Q + h * 128, PROJ + rowkn * NIN + PD_K + h * 128, PROJ + rowkn * NIN + PD_V + h * 128, 12, (char*)lds, C128, THR128, o,
.LBB0_366:
	s_lshr_b32 s0, s33, 8
	s_nop 0
	v_writelane_b32 v255, s0, 60
	s_ashr_i32 s0, s33, 7
	v_readlane_b32 s1, v254, 25
	s_add_i32 s2, s0, s1
	v_readlane_b32 s4, v254, 23
	v_med3_i32 v2, s2, 4, 60
	v_readlane_b32 s5, v254, 24
	v_readfirstlane_b32 s1, v2
	s_andn2_b64 vcc, exec, s[4:5]
	s_waitcnt lgkmcnt(0)
	s_cbranch_vccnz .LBB0_719
	v_and_b32_e32 v2, 31, v154
	s_lshr_b32 s3, s33, 1
	v_readlane_b32 s4, v252, 61
	v_readlane_b32 s6, v253, 6
	v_and_or_b32 v181, s3, 32, v2
	s_sub_i32 s3, s4, s2
	s_sub_i32 s2, s6, s2
	v_med3_i32 v4, s2, -7, 7
	s_movk_i32 s2, 0x1d1
	v_med3_i32 v3, s3, -7, 7
	v_cmp_gt_i32_e64 s[2:3], s2, v154
	s_add_i32 s8, s1, -4
	s_cmp_lt_u32 s4, s8
	v_writelane_b32 v255, s2, 26
	v_readlane_b32 s5, v252, 62
	v_med3_u32 v2, v181, 8, 56
	v_writelane_b32 v255, s3, 27
	s_cselect_b64 s[2:3], -1, 0
	s_add_i32 s9, s1, 4
	s_cmp_ge_u32 s4, s9
	s_cselect_b64 s[4:5], -1, 0
	s_or_b64 s[2:3], s[2:3], s[4:5]
	v_writelane_b32 v255, s2, 28
	s_movk_i32 s1, 0x7c
	v_add_u32_e32 v182, -8, v2
	v_writelane_b32 v255, s3, 29
	s_xor_b64 s[2:3], s[2:3], -1
	v_writelane_b32 v255, s2, 30
	s_cmp_lt_i32 s6, s8
	v_mul_lo_u32 v3, v3, s1
	v_writelane_b32 v255, s3, 31
	s_cselect_b64 s[2:3], -1, 0
	s_cmp_ge_u32 s6, s9
	v_writelane_b32 v255, s8, 32
	s_cselect_b64 s[4:5], -1, 0
	v_writelane_b32 v255, s9, 33
	s_or_b64 s[2:3], s[2:3], s[4:5]
	v_writelane_b32 v255, s2, 34
	v_add_u32_e32 v184, 8, v2
	v_subrev_u32_e32 v185, 24, v2
	v_writelane_b32 v255, s3, 35
	s_xor_b64 s[2:3], s[2:3], -1
	v_writelane_b32 v255, s2, 36
	v_mul_lo_u32 v2, v4, s1
	v_readlane_b32 s6, v252, 63
	v_writelane_b32 v255, s3, 37
	v_readlane_b32 s12, v254, 62
	v_readlane_b32 s8, v255, 14
	s_lshl_b32 s1, s8, 2
	v_readlane_b32 s7, v254, 56
	v_readlane_b32 s2, v254, 58
	s_or_b32 s1, s1, s6
	v_readlane_b32 s13, v254, 63
	v_readlane_b32 s14, v255, 0
	v_readlane_b32 s15, v255, 1
	v_readlane_b32 s16, v255, 2
	v_readlane_b32 s17, v255, 3
	v_readlane_b32 s18, v255, 4
	v_readlane_b32 s19, v255, 5
	v_add_u32_e32 v200, s7, v2
	v_readlane_b32 s3, v254, 59
	v_mov_b32_e32 v2, 0x3eb60549
	s_mov_b32 s5, s13
	s_mul_i32 s4, s1, 0x1d1
	v_readlane_b32 s12, v251, 9
	v_cndmask_b32_e64 v2, v250, v2, s[2:3]
	s_lshl_b64 s[2:3], s[4:5], 2
	v_readlane_b32 s14, v251, 11
	v_add_f32_e32 v0, v0, v11
	v_readlane_b32 s15, v251, 12
	s_add_u32 s2, s14, s2
	v_mul_f32_e32 v4, 0x3fb8aa3b, v0
	s_mov_b32 s1, 0x3fb8aa3b
	s_addc_u32 s3, s15, s3
	v_fma_f32 v5, v0, s1, -v4
	v_rndne_f32_e32 v6, v4
	v_readlane_b32 s9, v255, 15
	v_readlane_b32 s20, v255, 6
	v_readlane_b32 s21, v255, 7
	v_readlane_b32 s22, v255, 8
	v_readlane_b32 s23, v255, 9
	v_readlane_b32 s24, v255, 10
	v_readlane_b32 s25, v255, 11
	v_readlane_b32 s26, v255, 12
	v_readlane_b32 s27, v255, 13
	v_readlane_b32 s16, v251, 13
	v_readlane_b32 s17, v251, 14
	v_readlane_b32 s18, v251, 15
	v_readlane_b32 s19, v251, 16
	v_writelane_b32 v255, s2, 38
	v_fmac_f32_e32 v5, 0x32a5705f, v0
	v_sub_f32_e32 v4, v4, v6
	v_writelane_b32 v255, s3, 39
	s_lshl_b64 s[2:3], s[10:11], 2
	v_readlane_b32 s16, v251, 33
	v_add_f32_e32 v4, v4, v5
	v_readlane_b32 s17, v251, 34
	s_add_u32 s2, s16, s2
	v_exp_f32_e32 v4, v4
	v_cvt_i32_f32_e32 v5, v6
	s_addc_u32 s3, s17, s3
	v_writelane_b32 v255, s2, 40
	v_add_u32_e32 v183, s7, v3
	v_ldexp_f32 v4, v4, v5
	v_writelane_b32 v255, s3, 41
	s_mov_b32 s2, 0xc2ce8ed0
	v_cmp_ngt_f32_e32 vcc, s2, v0
	s_mov_b32 s3, 0x42b17218
	v_add_f32_e32 v3, v10, v12
	v_cndmask_b32_e32 v4, 0, v4, vcc
	v_cmp_nlt_f32_e32 vcc, s3, v0
	v_sub_f32_e32 v201, 1.0, v2
	v_lshlrev_b32_e32 v205, 2, v154
	v_cndmask_b32_e32 v0, v198, v4, vcc
	v_mul_f32_e32 v4, 0x3fb8aa3b, v3
	v_fma_f32 v5, v3, s1, -v4
	v_rndne_f32_e32 v6, v4
	v_fmac_f32_e32 v5, 0x32a5705f, v3
	v_sub_f32_e32 v4, v4, v6
	v_add_f32_e32 v4, v4, v5
	v_exp_f32_e32 v4, v4
	v_cvt_i32_f32_e32 v5, v6
	v_cmp_ngt_f32_e32 vcc, s2, v3
	s_movk_i32 s1, 0x1ff
	v_readlane_b32 s13, v251, 10
	v_ldexp_f32 v4, v4, v5
	v_cndmask_b32_e32 v4, 0, v4, vcc
	v_cmp_nlt_f32_e32 vcc, s3, v3
	v_add_u32_e32 v155, 0x200, v154
	v_readlane_b32 s18, v251, 35
	v_cndmask_b32_e32 v3, v198, v4, vcc
	v_sub_f32_e32 v0, v0, v3
	v_add_f32_e32 v202, v2, v0
	v_max_i32_e32 v0, 0xffffffd1, v154
	v_sub_u32_e32 v0, v0, v154
	v_add_u32_e32 v0, 0x1ff, v0
	v_lshrrev_b32_e32 v2, 9, v0
	v_add_u32_e32 v2, 1, v2
	v_cmp_lt_u32_e64 s[2:3], s1, v0
	v_and_b32_e32 v203, 0xfffffe, v2
	v_readlane_b32 s1, v254, 57
	v_writelane_b32 v255, s2, 42
	v_lshl_add_u32 v204, v203, 9, v154
	v_add_u32_e32 v206, s1, v205
	v_writelane_b32 v255, s3, 43
	v_cmp_ne_u32_e64 s[2:3], v2, v203
	s_mul_i32 s1, s8, 0x744
	v_readlane_b32 s19, v251, 36
	v_writelane_b32 v255, s2, 44
	v_readlane_b32 s20, v251, 37
	v_readlane_b32 s21, v251, 38
	v_writelane_b32 v255, s3, 45
	s_mul_i32 s2, s6, 0x1d1
	s_add_i32 s4, s2, s1
	s_mov_b32 s1, s5
	v_writelane_b32 v254, s0, 62
	v_readlane_b32 s22, v251, 39
	v_readlane_b32 s23, v251, 40
	v_writelane_b32 v255, s2, 0
	v_writelane_b32 v255, s3, 1
	v_writelane_b32 v255, s4, 2
	v_writelane_b32 v255, s5, 3
	v_writelane_b32 v255, s6, 4
	v_writelane_b32 v255, s7, 5
	v_writelane_b32 v255, s8, 6
	v_writelane_b32 v255, s9, 7
	v_writelane_b32 v255, s10, 8
	v_writelane_b32 v255, s11, 9
	v_writelane_b32 v255, s12, 10
	v_writelane_b32 v255, s13, 11
	v_writelane_b32 v255, s14, 12
	v_writelane_b32 v255, s15, 13
	s_lshl_b64 s[2:3], s[4:5], 2
	s_add_u32 s2, s14, s2
	v_writelane_b32 v254, s1, 63
	s_addc_u32 s3, s15, s3
	v_writelane_b32 v255, s2, 46
	v_readlane_b32 s1, v254, 27
	s_sub_i32 s0, s1, s0
	v_writelane_b32 v255, s3, 47
	v_writelane_b32 v255, s0, 48
	s_mov_b32 s3, 0
	v_readlane_b32 s2, v251, 0
	v_readlane_b32 s24, v251, 41
	v_readlane_b32 s25, v251, 42
	v_readlane_b32 s26, v251, 43
	v_readlane_b32 s27, v251, 44
	v_readlane_b32 s28, v251, 45
	v_readlane_b32 s29, v251, 46
	v_readlane_b32 s30, v251, 47
	v_readlane_b32 s31, v251, 48
	s_branch .LBB0_370

; #define SWAIT() do { if (SD == 1) asm volatile("s_waitcnt vmcnt(0)" ::: "memory"); else if (DK == 128) asm volatile("s_waitcnt vmcnt(4)" ::: "memory"); else asm volatile("s_waitcnt vmcnt(3)" ::: "memory"); } while (0)
; __device__ __forceinline__ void partialSM(f32x16& p0, f32x16& p1, float& m_reg, float& mn, float& alpha, float C, float thrRaw) {
;     ...
;   float mnC = -mn * C;
; #pragma unroll
;   for (int r = 0; r < 16; ++r) p0[r] = fmaf(p0[r], C, mnC);
; #pragma unroll
;   for (int r = 0; r < 16; ++r) p1[r] = fmaf(p1[r], C, mnC);
; #pragma unroll
;   for (int r = 0; r < 16; ++r) p0[r] = __builtin_amdgcn_exp2f(p0[r]);
; template <int DK, bool NA, bool QL, int SD> ...
;     ...
;     __syncthreads(); SWAIT(); SWRITE(0, SE);
.LBB0_686:
	v_readlane_b32 s6, v255, 60
	s_nop 3
	s_cmp_lg_u32 s6, 0
	s_cbranch_scc1 .Lstg_d1_a
	v_cndmask_b32_e64 v223, v138, v142, s[2:3]
	v_mul_f32_e32 v224, 0xbe38aa3b, v223
	v_fmamk_f32 v82, v82, 0x3e38aa3b, v224
	v_fmamk_f32 v83, v83, 0x3e38aa3b, v224
	v_fmamk_f32 v84, v84, 0x3e38aa3b, v224
	v_fmamk_f32 v85, v85, 0x3e38aa3b, v224
	v_fmamk_f32 v86, v86, 0x3e38aa3b, v224
	v_fmamk_f32 v87, v87, 0x3e38aa3b, v224
	v_fmamk_f32 v88, v88, 0x3e38aa3b, v224
	v_fmamk_f32 v89, v89, 0x3e38aa3b, v224
	v_fmamk_f32 v90, v90, 0x3e38aa3b, v224
	v_fmamk_f32 v91, v91, 0x3e38aa3b, v224
	v_fmamk_f32 v92, v92, 0x3e38aa3b, v224
	v_fmamk_f32 v93, v93, 0x3e38aa3b, v224
	v_fmamk_f32 v94, v94, 0x3e38aa3b, v224
	v_fmamk_f32 v95, v95, 0x3e38aa3b, v224
	v_fmamk_f32 v96, v96, 0x3e38aa3b, v224
	v_fmamk_f32 v97, v97, 0x3e38aa3b, v224
	v_exp_f32_e32 v138, v82
	v_exp_f32_e32 v153, v83
	v_exp_f32_e32 v139, v84
	v_exp_f32_e32 v152, v85
	v_exp_f32_e32 v140, v86
	v_exp_f32_e32 v151, v87
	v_exp_f32_e32 v141, v88
	v_exp_f32_e32 v150, v89
	v_exp_f32_e32 v142, v90
	v_exp_f32_e32 v149, v91
	v_exp_f32_e32 v143, v92
	v_exp_f32_e32 v148, v93
	v_exp_f32_e32 v144, v94
	v_exp_f32_e32 v147, v95
	v_exp_f32_e32 v145, v96
	v_exp_f32_e32 v146, v97
	v_fmamk_f32 v233, v66, 0x3e38aa3b, v224
	v_fmamk_f32 v234, v67, 0x3e38aa3b, v224
	v_fmamk_f32 v235, v68, 0x3e38aa3b, v224
	v_fmamk_f32 v236, v69, 0x3e38aa3b, v224
	v_fmamk_f32 v237, v70, 0x3e38aa3b, v224
	v_fmamk_f32 v226, v71, 0x3e38aa3b, v224
	v_fmamk_f32 v227, v72, 0x3e38aa3b, v224
	v_fmamk_f32 v228, v73, 0x3e38aa3b, v224
	v_fmamk_f32 v229, v74, 0x3e38aa3b, v224
	v_fmamk_f32 v230, v75, 0x3e38aa3b, v224
	v_fmamk_f32 v231, v76, 0x3e38aa3b, v224
	v_fmamk_f32 v232, v77, 0x3e38aa3b, v224
	v_fmamk_f32 v225, v78, 0x3e38aa3b, v224
	v_fmamk_f32 v238, v79, 0x3e38aa3b, v224
	v_fmamk_f32 v239, v80, 0x3e38aa3b, v224
	v_fmac_f32_e32 v224, 0x3e38aa3b, v81
.Lstg_d1_a:
	s_waitcnt lgkmcnt(0)
	s_barrier
	s_cmp_eq_u32 s6, 0
	s_cbranch_scc1 .Lstg_d1_b
	v_cndmask_b32_e64 v223, v138, v142, s[2:3]
	v_mul_f32_e32 v224, 0xbe38aa3b, v223
	v_fmamk_f32 v82, v82, 0x3e38aa3b, v224
	v_fmamk_f32 v83, v83, 0x3e38aa3b, v224
	v_fmamk_f32 v84, v84, 0x3e38aa3b, v224
	v_fmamk_f32 v85, v85, 0x3e38aa3b, v224
	v_fmamk_f32 v86, v86, 0x3e38aa3b, v224
	v_fmamk_f32 v87, v87, 0x3e38aa3b, v224
	v_fmamk_f32 v88, v88, 0x3e38aa3b, v224
	v_fmamk_f32 v89, v89, 0x3e38aa3b, v224
	v_fmamk_f32 v90, v90, 0x3e38aa3b, v224
	v_fmamk_f32 v91, v91, 0x3e38aa3b, v224
	v_fmamk_f32 v92, v92, 0x3e38aa3b, v224
	v_fmamk_f32 v93, v93, 0x3e38aa3b, v224
	v_fmamk_f32 v94, v94, 0x3e38aa3b, v224
	v_fmamk_f32 v95, v95, 0x3e38aa3b, v224
	v_fmamk_f32 v96, v96, 0x3e38aa3b, v224
	v_fmamk_f32 v97, v97, 0x3e38aa3b, v224
	v_exp_f32_e32 v138, v82
	v_exp_f32_e32 v153, v83
	v_exp_f32_e32 v139, v84
	v_exp_f32_e32 v152, v85
	v_exp_f32_e32 v140, v86
	v_exp_f32_e32 v151, v87
	v_exp_f32_e32 v141, v88
	v_exp_f32_e32 v150, v89
	v_exp_f32_e32 v142, v90
	v_exp_f32_e32 v149, v91
	v_exp_f32_e32 v143, v92
	v_exp_f32_e32 v148, v93
	v_exp_f32_e32 v144, v94
	v_exp_f32_e32 v147, v95
	v_exp_f32_e32 v145, v96
	v_exp_f32_e32 v146, v97
	v_fmamk_f32 v233, v66, 0x3e38aa3b, v224
	v_fmamk_f32 v234, v67, 0x3e38aa3b, v224
	v_fmamk_f32 v235, v68, 0x3e38aa3b, v224
	v_fmamk_f32 v236, v69, 0x3e38aa3b, v224
	v_fmamk_f32 v237, v70, 0x3e38aa3b, v224
	v_fmamk_f32 v226, v71, 0x3e38aa3b, v224
	v_fmamk_f32 v227, v72, 0x3e38aa3b, v224
	v_fmamk_f32 v228, v73, 0x3e38aa3b, v224
	v_fmamk_f32 v229, v74, 0x3e38aa3b, v224
	v_fmamk_f32 v230, v75, 0x3e38aa3b, v224
	v_fmamk_f32 v231, v76, 0x3e38aa3b, v224
	v_fmamk_f32 v232, v77, 0x3e38aa3b, v224
	v_fmamk_f32 v225, v78, 0x3e38aa3b, v224
	v_fmamk_f32 v238, v79, 0x3e38aa3b, v224
	v_fmamk_f32 v239, v80, 0x3e38aa3b, v224
	v_fmac_f32_e32 v224, 0x3e38aa3b, v81
; __device__ __forceinline__ void finishSM(f32x16& p0, f32x16& p1, float alpha, float& l_reg, bf16x8& pa0, bf16x8& pa1, bf16x8& pa2, bf16x8& pa3) {
; #pragma unroll
;   for (int r = 0; r < 16; ++r) p1[r] = __builtin_amdgcn_exp2f(p1[r]);
;   float ps = 0;
; #pragma unroll
;   for (int r = 0; r < 16; ++r) ps += p0[r];
; #pragma unroll
;   for (int r = 0; r < 16; ++r) ps += p1[r];
;   { auto rr = __builtin_amdgcn_permlane32_swap(__float_as_uint(ps), __float_as_uint(ps), false, false);
;     ps = __uint_as_float(rr[0]) + __uint_as_float(rr[1]); }
;   l_reg = l_reg * alpha + ps;
;     ...
;   PK4(p0, 0, pa0); PK4(p0, 8, pa1); PK4(p1, 0, pa2); PK4(p1, 8, pa3);
; template <int DK, bool QL>
; __device__ __forceinline__ void qkt(f32x16& p0, f32x16& p1, const bf16* Ks, const bf16x8* qr, const char* ql, int r32, int hi) {
;   p0 = f32x16{}; p1 = f32x16{};
; #pragma unroll
;   for (int d0 = 0; d0 < DK / 16; ++d0) { int cb = (d0 * 16 + hi * 8) * 2;
;     const bf16x8 qv = QL ? *reinterpret_cast<const bf16x8*>(ql + d0 * 1024) : qr[d0];
;     bf16x8 b0 = *reinterpret_cast<const bf16x8*>((const char*)Ks + kswz<DK>(r32, cb));
;     bf16x8 b1 = *reinterpret_cast<const bf16x8*>((const char*)Ks + kswz<DK>(32 + r32, cb));
;     p0 = __builtin_amdgcn_mfma_f32_32x32x16_bf16(b0, qv, p0, 0, 0, 0);
;     p1 = __builtin_amdgcn_mfma_f32_32x32x16_bf16(b1, qv, p1, 0, 0, 0); }
.Lstg_d1_b:
	ds_read_b128 v[66:69], v212 offset:32768
	ds_read_b128 v[70:73], v212 offset:36864
	v_exp_f32_e32 v164, v233
	v_exp_f32_e32 v233, v224
	v_add_f32_e32 v224, 0, v138
	v_add_f32_e32 v224, v153, v224
	s_waitcnt lgkmcnt(1)
	v_mfma_f32_32x32x16_bf16 v[82:97], v[66:69], v[110:113], 0
	v_add_f32_e32 v224, v139, v224
	v_add_f32_e32 v224, v152, v224
	v_add_f32_e32 v224, v140, v224
	ds_read_b128 v[240:243], v216 offset:32768
	ds_read_b128 v[244:247], v216 offset:36864
	v_add_f32_e32 v224, v151, v224
	v_add_f32_e32 v224, v141, v224
	v_add_f32_e32 v224, v150, v224
	s_waitcnt lgkmcnt(2)
	v_mfma_f32_32x32x16_bf16 v[66:81], v[70:73], v[110:113], 0
	v_add_f32_e32 v224, v142, v224
	v_add_f32_e32 v224, v149, v224
	v_add_f32_e32 v224, v143, v224
	v_add_f32_e32 v224, v148, v224
	v_add_f32_e32 v224, v144, v224
	v_exp_f32_e32 v165, v234
	v_add_f32_e32 v224, v147, v224
	s_waitcnt lgkmcnt(1)
	v_mfma_f32_32x32x16_bf16 v[82:97], v[240:243], v[106:109], v[82:97]
	v_exp_f32_e32 v166, v235
	v_add_f32_e32 v224, v145, v224
	v_exp_f32_e32 v167, v236
	v_add_f32_e32 v224, v146, v224
	v_exp_f32_e32 v172, v237
	v_add_f32_e32 v224, v164, v224
	v_exp_f32_e32 v173, v226
	s_waitcnt lgkmcnt(0)
	v_mfma_f32_32x32x16_bf16 v[66:81], v[244:247], v[106:109], v[66:81]
	ds_read_b128 v[240:243], v217 offset:32768
	ds_read_b128 v[244:247], v217 offset:36864
	v_add_f32_e32 v224, v165, v224
	v_exp_f32_e32 v174, v227
	v_add_f32_e32 v224, v166, v224
	v_exp_f32_e32 v175, v228
	v_add_f32_e32 v224, v167, v224
	v_exp_f32_e32 v226, v229
	s_waitcnt lgkmcnt(1)
	v_mfma_f32_32x32x16_bf16 v[82:97], v[240:243], v[98:101], v[82:97]
	v_add_f32_e32 v224, v172, v224
	v_exp_f32_e32 v227, v230
	v_add_f32_e32 v224, v173, v224
	v_exp_f32_e32 v228, v231
	v_add_f32_e32 v224, v174, v224
	v_exp_f32_e32 v229, v232
	v_add_f32_e32 v224, v175, v224
	s_waitcnt lgkmcnt(0)
	v_mfma_f32_32x32x16_bf16 v[66:81], v[244:247], v[98:101], v[66:81]
	ds_read_b128 v[240:243], v218 offset:32768
	ds_read_b128 v[244:247], v218 offset:36864
	v_exp_f32_e32 v230, v225
	v_add_f32_e32 v224, v226, v224
	v_exp_f32_e32 v231, v238
	v_add_f32_e32 v224, v227, v224
	v_exp_f32_e32 v232, v239
	v_add_f32_e32 v224, v228, v224
	s_waitcnt lgkmcnt(1)
	v_mfma_f32_32x32x16_bf16 v[82:97], v[240:243], v[102:105], v[82:97]
	v_add_f32_e32 v224, v229, v224
	v_add_f32_e32 v224, v230, v224
	v_add_f32_e32 v224, v231, v224
	v_add_f32_e32 v224, v232, v224
	v_add_f32_e32 v224, v233, v224
	v_mov_b32_e32 v225, v224
	v_cvt_pk_bf16_f32 v138, v138, v153
	s_waitcnt lgkmcnt(0)
	v_mfma_f32_32x32x16_bf16 v[66:81], v[244:247], v[102:105], v[66:81]
	v_cvt_pk_bf16_f32 v139, v139, v152
	v_cvt_pk_bf16_f32 v140, v140, v151
	v_cvt_pk_bf16_f32 v141, v141, v150
	v_cvt_pk_bf16_f32 v142, v142, v149
	v_cvt_pk_bf16_f32 v143, v143, v148
	v_cvt_pk_bf16_f32 v144, v144, v147
	v_cvt_pk_bf16_f32 v145, v145, v146
	v_cvt_pk_bf16_f32 v146, v164, v165
	v_cvt_pk_bf16_f32 v147, v166, v167
	v_cvt_pk_bf16_f32 v148, v172, v173
	v_cvt_pk_bf16_f32 v149, v174, v175
	v_cvt_pk_bf16_f32 v150, v226, v227
	v_cvt_pk_bf16_f32 v151, v228, v229
	v_cvt_pk_bf16_f32 v152, v230, v231
	v_cvt_pk_bf16_f32 v153, v232, v233
	v_permlane32_swap_b32_e32 v224, v225
	v_permlane32_swap_b32_e32 v138, v140
	v_permlane32_swap_b32_e32 v139, v141
	v_permlane32_swap_b32_e32 v142, v144
	v_permlane32_swap_b32_e32 v143, v145
	v_permlane32_swap_b32_e32 v146, v148
	v_permlane32_swap_b32_e32 v147, v149
	v_permlane32_swap_b32_e32 v150, v152
	v_permlane32_swap_b32_e32 v151, v153
	s_cmp_gt_u32 s9, 60
	s_cselect_b64 s[4:5], -1, 0
	s_and_b64 vcc, exec, s[4:5]
	s_cbranch_vccnz .LBB0_688
	v_add_co_u32_e32 v114, vcc, 0xe180000, v160
	s_nop 1
	v_addc_co_u32_e32 v115, vcc, 0, v161, vcc
	v_add_co_u32_e32 v118, vcc, 0xe1d0000, v160
	s_nop 1
	v_addc_co_u32_e32 v119, vcc, 0, v161, vcc
	v_add_co_u32_e32 v122, vcc, 0xe180000, v176
	global_load_dwordx4 v[114:117], v[114:115], off offset:2048
	s_nop 0
	global_load_dwordx4 v[118:121], v[118:119], off offset:2048
	v_addc_co_u32_e32 v123, vcc, 0, v177, vcc
	global_load_dwordx4 v[122:125], v[122:123], off offset:1024

; __device__ __forceinline__ void finishSM(f32x16& p0, f32x16& p1, float alpha, float& l_reg, bf16x8& pa0, bf16x8& pa1, bf16x8& pa2, bf16x8& pa3) {
; #pragma unroll
;   for (int r = 0; r < 16; ++r) p1[r] = __builtin_amdgcn_exp2f(p1[r]);
;   float ps = 0;
; #pragma unroll
;   for (int r = 0; r < 16; ++r) ps += p0[r];
; #pragma unroll
;   for (int r = 0; r < 16; ++r) ps += p1[r];
;   { auto rr = __builtin_amdgcn_permlane32_swap(__float_as_uint(ps), __float_as_uint(ps), false, false);
;     ps = __uint_as_float(rr[0]) + __uint_as_float(rr[1]); }
;   l_reg = l_reg * alpha + ps;
;     ...
;   PK4(p0, 0, pa0); PK4(p0, 8, pa1); PK4(p1, 0, pa2); PK4(p1, 8, pa3);
; template <int DK, bool QL>
; __device__ __forceinline__ void qkt(f32x16& p0, f32x16& p1, const bf16* Ks, const bf16x8* qr, const char* ql, int r32, int hi) {
;   p0 = f32x16{}; p1 = f32x16{};
; #pragma unroll
;   for (int d0 = 0; d0 < DK / 16; ++d0) { int cb = (d0 * 16 + hi * 8) * 2;
;     const bf16x8 qv = QL ? *reinterpret_cast<const bf16x8*>(ql + d0 * 1024) : qr[d0];
;     bf16x8 b0 = *reinterpret_cast<const bf16x8*>((const char*)Ks + kswz<DK>(r32, cb));
;     bf16x8 b1 = *reinterpret_cast<const bf16x8*>((const char*)Ks + kswz<DK>(32 + r32, cb));
;     p0 = __builtin_amdgcn_mfma_f32_32x32x16_bf16(b0, qv, p0, 0, 0, 0);
;     p1 = __builtin_amdgcn_mfma_f32_32x32x16_bf16(b1, qv, p1, 0, 0, 0); }
.Lstg_d2_b:
	ds_read_b128 v[66:69], v215 offset:32768
	ds_read_b128 v[70:73], v215 offset:36864
	v_exp_f32_e32 v164, v233
	v_exp_f32_e32 v233, v224
	v_add_f32_e32 v224, 0, v138
	v_add_f32_e32 v224, v153, v224
	s_waitcnt lgkmcnt(1)
	v_mfma_f32_32x32x16_bf16 v[82:97], v[66:69], v[110:113], 0
	v_add_f32_e32 v224, v139, v224
	v_add_f32_e32 v224, v152, v224
	v_add_f32_e32 v224, v140, v224
	ds_read_b128 v[240:243], v216 offset:32768
	ds_read_b128 v[244:247], v216 offset:36864
	v_add_f32_e32 v224, v151, v224
	v_add_f32_e32 v224, v141, v224
	v_add_f32_e32 v224, v150, v224
	s_waitcnt lgkmcnt(2)
	v_mfma_f32_32x32x16_bf16 v[66:81], v[70:73], v[110:113], 0
	v_add_f32_e32 v224, v142, v224
	v_add_f32_e32 v224, v149, v224
	v_add_f32_e32 v224, v143, v224
	v_add_f32_e32 v224, v148, v224
	v_add_f32_e32 v224, v144, v224
	v_exp_f32_e32 v165, v234
	v_add_f32_e32 v224, v147, v224
	s_waitcnt lgkmcnt(1)
	v_mfma_f32_32x32x16_bf16 v[82:97], v[240:243], v[106:109], v[82:97]
	v_exp_f32_e32 v166, v235
	v_add_f32_e32 v224, v145, v224
	v_exp_f32_e32 v167, v236
	v_add_f32_e32 v224, v146, v224
	v_exp_f32_e32 v172, v237
	v_add_f32_e32 v224, v164, v224
	v_exp_f32_e32 v173, v226
	s_waitcnt lgkmcnt(0)
	v_mfma_f32_32x32x16_bf16 v[66:81], v[244:247], v[106:109], v[66:81]
	ds_read_b128 v[240:243], v217 offset:32768
	ds_read_b128 v[244:247], v217 offset:36864
	v_add_f32_e32 v224, v165, v224
	v_exp_f32_e32 v174, v227
	v_add_f32_e32 v224, v166, v224
	v_exp_f32_e32 v175, v228
	v_add_f32_e32 v224, v167, v224
	v_exp_f32_e32 v226, v229
	s_waitcnt lgkmcnt(1)
	v_mfma_f32_32x32x16_bf16 v[82:97], v[240:243], v[102:105], v[82:97]
	v_add_f32_e32 v224, v172, v224
	v_exp_f32_e32 v227, v230
	v_add_f32_e32 v224, v173, v224
	v_exp_f32_e32 v228, v231
	v_add_f32_e32 v224, v174, v224
	v_exp_f32_e32 v229, v232
	v_add_f32_e32 v224, v175, v224
	s_waitcnt lgkmcnt(0)
	v_mfma_f32_32x32x16_bf16 v[66:81], v[244:247], v[102:105], v[66:81]
	ds_read_b128 v[240:243], v218 offset:32768
	ds_read_b128 v[244:247], v218 offset:36864
	v_exp_f32_e32 v230, v225
	v_add_f32_e32 v224, v226, v224
	v_exp_f32_e32 v231, v238
	v_add_f32_e32 v224, v227, v224
	v_exp_f32_e32 v232, v239
	v_add_f32_e32 v224, v228, v224
	s_waitcnt lgkmcnt(1)
	v_mfma_f32_32x32x16_bf16 v[82:97], v[240:243], v[98:101], v[82:97]
	v_add_f32_e32 v224, v229, v224
	v_add_f32_e32 v224, v230, v224
	v_add_f32_e32 v224, v231, v224
	v_add_f32_e32 v224, v232, v224
	v_add_f32_e32 v224, v233, v224
	v_mov_b32_e32 v225, v224
	v_cvt_pk_bf16_f32 v138, v138, v153
	s_waitcnt lgkmcnt(0)
	v_mfma_f32_32x32x16_bf16 v[66:81], v[244:247], v[98:101], v[66:81]
	v_cvt_pk_bf16_f32 v139, v139, v152
	v_cvt_pk_bf16_f32 v140, v140, v151
	v_cvt_pk_bf16_f32 v141, v141, v150
	v_cvt_pk_bf16_f32 v142, v142, v149
	v_cvt_pk_bf16_f32 v143, v143, v148
	v_cvt_pk_bf16_f32 v144, v144, v147
	v_cvt_pk_bf16_f32 v145, v145, v146
	v_cvt_pk_bf16_f32 v146, v164, v165
	v_cvt_pk_bf16_f32 v147, v166, v167
	v_cvt_pk_bf16_f32 v148, v172, v173
	v_cvt_pk_bf16_f32 v149, v174, v175
	v_cvt_pk_bf16_f32 v150, v226, v227
	v_cvt_pk_bf16_f32 v151, v228, v229
	v_cvt_pk_bf16_f32 v152, v230, v231
	v_cvt_pk_bf16_f32 v153, v232, v233
	v_permlane32_swap_b32_e32 v224, v225
	v_permlane32_swap_b32_e32 v138, v140
	v_permlane32_swap_b32_e32 v139, v141
	v_permlane32_swap_b32_e32 v142, v144
	v_permlane32_swap_b32_e32 v143, v145
	v_permlane32_swap_b32_e32 v146, v148
	v_permlane32_swap_b32_e32 v147, v149
	v_permlane32_swap_b32_e32 v150, v152
	v_permlane32_swap_b32_e32 v151, v153
	s_cmp_gt_u32 s8, 60
	s_cselect_b64 s[4:5], -1, 0
	s_and_b64 vcc, exec, s[4:5]
	s_cbranch_vccnz .LBB0_707
	v_add_co_u32_e32 v114, vcc, 0xe180000, v160
	s_nop 1
	v_addc_co_u32_e32 v115, vcc, 0, v161, vcc
	v_add_co_u32_e32 v118, vcc, 0xe1d0000, v160
	s_nop 1
	v_addc_co_u32_e32 v119, vcc, 0, v161, vcc
	v_add_co_u32_e32 v122, vcc, 0xe180000, v176
	global_load_dwordx4 v[114:117], v[114:115], off offset:2048
	s_nop 0
	global_load_dwordx4 v[118:121], v[118:119], off offset:2048
	v_addc_co_u32_e32 v123, vcc, 0, v177, vcc
	global_load_dwordx4 v[122:125], v[122:123], off offset:1152
